# trailing half at fixed priority 1 for the whole K-loop (per-block s_setprio flips removed) on top of k-snake + scalar-base DMA addressing
# baseline (speedup 1.0000x reference)
.Lprio_skip_1:
.LBB0_169:
	s_add_u32 s34, s50, 0xfff80080
	s_addc_u32 s35, s51, -1
	s_add_i32 s52, 0, 0x10000
	s_cmp_eq_u32 s77, 28
	s_cselect_b32 s55, s36, s35
	s_cselect_b32 s54, s37, s34
	v_add_u32_e32 v145, s52, v142
	s_cselect_b32 s35, s41, s76
	s_cselect_b32 s34, s43, s71
	s_add_i32 s53, 0, 0x14000
	ds_read_b128 v[146:149], v145
	ds_read_b128 v[150:153], v145 offset:1024
	ds_read_b128 v[172:175], v145 offset:2048
	ds_read_b128 v[176:179], v145 offset:3072
	v_add_u32_e32 v145, s53, v142
	ds_read_b128 v[180:183], v145
	ds_read_b128 v[184:187], v145 offset:1024
	ds_read_b128 v[188:191], v145 offset:2048
	ds_read_b128 v[192:195], v145 offset:3072
	s_add_i32 m0, s57, 0xc000
	ds_read_b128 v[196:199], v144
	ds_read_b128 v[200:203], v144 offset:1024
	ds_read_b128 v[204:207], v144 offset:2048
	ds_read_b128 v[208:211], v144 offset:3072
	ds_read_b128 v[212:215], v144 offset:4096
	ds_read_b128 v[216:219], v144 offset:5120
	ds_read_b128 v[228:231], v144 offset:6144
	ds_read_b128 v[232:235], v144 offset:7168
	global_load_lds_dwordx4 v138, s[50:51]
	s_add_i32 m0, s57, 0xe000
	s_nop 0
	global_load_lds_dwordx4 v140, s[50:51]
	s_waitcnt vmcnt(8)
	s_waitcnt lgkmcnt(0)
	s_barrier
	v_mfma_f32_16x16x32_bf16 v[128:131], v[146:149], v[196:199], v[128:131]
	v_mfma_f32_16x16x32_bf16 v[128:131], v[150:153], v[200:203], v[128:131]
	v_mfma_f32_16x16x32_bf16 v[124:127], v[176:179], v[200:203], v[124:127]
	v_mfma_f32_16x16x32_bf16 v[124:127], v[172:175], v[196:199], v[124:127]
	v_mfma_f32_16x16x32_bf16 v[108:111], v[172:175], v[204:207], v[108:111]
	v_mfma_f32_16x16x32_bf16 v[108:111], v[176:179], v[208:211], v[108:111]
	v_mfma_f32_16x16x32_bf16 v[112:115], v[150:153], v[208:211], v[112:115]
	v_mfma_f32_16x16x32_bf16 v[112:115], v[146:149], v[204:207], v[112:115]
	v_mfma_f32_16x16x32_bf16 v[96:99], v[146:149], v[212:215], v[96:99]
	v_mfma_f32_16x16x32_bf16 v[96:99], v[150:153], v[216:219], v[96:99]
	v_mfma_f32_16x16x32_bf16 v[92:95], v[176:179], v[216:219], v[92:95]
	v_mfma_f32_16x16x32_bf16 v[92:95], v[172:175], v[212:215], v[92:95]
	v_mfma_f32_16x16x32_bf16 v[76:79], v[172:175], v[228:231], v[76:79]
	v_mfma_f32_16x16x32_bf16 v[76:79], v[176:179], v[232:235], v[76:79]
	v_mfma_f32_16x16x32_bf16 v[80:83], v[150:153], v[232:235], v[80:83]
	v_mfma_f32_16x16x32_bf16 v[80:83], v[146:149], v[228:231], v[80:83]
	v_mfma_f32_16x16x32_bf16 v[120:123], v[180:183], v[196:199], v[120:123]
	v_mfma_f32_16x16x32_bf16 v[120:123], v[184:187], v[200:203], v[120:123]
	v_mfma_f32_16x16x32_bf16 v[116:119], v[192:195], v[200:203], v[116:119]
	v_mfma_f32_16x16x32_bf16 v[116:119], v[188:191], v[196:199], v[116:119]
	v_mfma_f32_16x16x32_bf16 v[100:103], v[188:191], v[204:207], v[100:103]
	v_mfma_f32_16x16x32_bf16 v[100:103], v[192:195], v[208:211], v[100:103]
	v_mfma_f32_16x16x32_bf16 v[104:107], v[184:187], v[208:211], v[104:107]
	v_mfma_f32_16x16x32_bf16 v[104:107], v[180:183], v[204:207], v[104:107]
	v_mfma_f32_16x16x32_bf16 v[88:91], v[180:183], v[212:215], v[88:91]
	v_mfma_f32_16x16x32_bf16 v[88:91], v[184:187], v[216:219], v[88:91]
	v_mfma_f32_16x16x32_bf16 v[84:87], v[192:195], v[216:219], v[84:87]
	v_mfma_f32_16x16x32_bf16 v[84:87], v[188:191], v[212:215], v[84:87]
	v_mfma_f32_16x16x32_bf16 v[68:71], v[188:191], v[228:231], v[68:71]
	v_mfma_f32_16x16x32_bf16 v[68:71], v[192:195], v[232:235], v[68:71]
	v_mfma_f32_16x16x32_bf16 v[72:75], v[184:187], v[232:235], v[72:75]
	v_mfma_f32_16x16x32_bf16 v[72:75], v[180:183], v[228:231], v[72:75]
	s_barrier
	s_add_u32 s100, s54, s14
	s_addc_u32 s101, s55, s15
	s_add_i32 s52, s52, s19
	s_mov_b32 m0, s52
	ds_read_b128 v[196:199], v144 offset:16384
	ds_read_b128 v[200:203], v144 offset:17408
	ds_read_b128 v[204:207], v144 offset:18432
	ds_read_b128 v[208:211], v144 offset:19456
	ds_read_b128 v[212:215], v144 offset:20480
	ds_read_b128 v[216:219], v144 offset:21504
	ds_read_b128 v[228:231], v144 offset:22528
	ds_read_b128 v[232:235], v144 offset:23552
	global_load_lds_dwordx4 v134, s[34:35]
	s_add_i32 m0, s52, 0x2000
	s_add_u32 s96, s34, 0x4000
	s_addc_u32 s97, s35, 0
	s_add_i32 s52, s53, s19
	global_load_lds_dwordx4 v0, s[34:35]
	s_mov_b32 m0, s52
	s_nop 0
	global_load_lds_dwordx4 v134, s[96:97]
	s_add_i32 m0, s52, 0x2000
	s_nop 0
	global_load_lds_dwordx4 v0, s[96:97]
	s_mov_b32 m0, s57
	s_nop 0
	global_load_lds_dwordx4 v136, s[54:55]
	s_mov_b32 m0, s58
	s_nop 0
	global_load_lds_dwordx4 v132, s[54:55]
	s_waitcnt vmcnt(8)
	s_waitcnt lgkmcnt(0)
	s_barrier
	v_mfma_f32_16x16x32_bf16 v[64:67], v[146:149], v[196:199], v[64:67]
	v_mfma_f32_16x16x32_bf16 v[64:67], v[150:153], v[200:203], v[64:67]
	v_mfma_f32_16x16x32_bf16 v[60:63], v[176:179], v[200:203], v[60:63]
	v_mfma_f32_16x16x32_bf16 v[60:63], v[172:175], v[196:199], v[60:63]
	v_mfma_f32_16x16x32_bf16 v[44:47], v[172:175], v[204:207], v[44:47]
	v_mfma_f32_16x16x32_bf16 v[44:47], v[176:179], v[208:211], v[44:47]
	v_mfma_f32_16x16x32_bf16 v[48:51], v[150:153], v[208:211], v[48:51]
	v_mfma_f32_16x16x32_bf16 v[48:51], v[146:149], v[204:207], v[48:51]
	v_mfma_f32_16x16x32_bf16 v[32:35], v[146:149], v[212:215], v[32:35]
	v_mfma_f32_16x16x32_bf16 v[32:35], v[150:153], v[216:219], v[32:35]
	v_mfma_f32_16x16x32_bf16 v[28:31], v[176:179], v[216:219], v[28:31]
	v_mfma_f32_16x16x32_bf16 v[28:31], v[172:175], v[212:215], v[28:31]
	v_mfma_f32_16x16x32_bf16 v[12:15], v[172:175], v[228:231], v[12:15]
	v_mfma_f32_16x16x32_bf16 v[12:15], v[176:179], v[232:235], v[12:15]
	v_mfma_f32_16x16x32_bf16 v[16:19], v[150:153], v[232:235], v[16:19]
	v_mfma_f32_16x16x32_bf16 v[16:19], v[146:149], v[228:231], v[16:19]
	v_mfma_f32_16x16x32_bf16 v[56:59], v[180:183], v[196:199], v[56:59]
	v_mfma_f32_16x16x32_bf16 v[56:59], v[184:187], v[200:203], v[56:59]
	v_mfma_f32_16x16x32_bf16 v[52:55], v[192:195], v[200:203], v[52:55]
	v_mfma_f32_16x16x32_bf16 v[52:55], v[188:191], v[196:199], v[52:55]
	v_mfma_f32_16x16x32_bf16 v[36:39], v[188:191], v[204:207], v[36:39]
	v_mfma_f32_16x16x32_bf16 v[36:39], v[192:195], v[208:211], v[36:39]
	v_mfma_f32_16x16x32_bf16 v[40:43], v[184:187], v[208:211], v[40:43]
	v_mfma_f32_16x16x32_bf16 v[40:43], v[180:183], v[204:207], v[40:43]
	v_mfma_f32_16x16x32_bf16 v[24:27], v[180:183], v[212:215], v[24:27]
	v_mfma_f32_16x16x32_bf16 v[24:27], v[184:187], v[216:219], v[24:27]
	v_mfma_f32_16x16x32_bf16 v[20:23], v[192:195], v[216:219], v[20:23]
	v_mfma_f32_16x16x32_bf16 v[20:23], v[188:191], v[212:215], v[20:23]
	v_mfma_f32_16x16x32_bf16 v[4:7], v[188:191], v[228:231], v[4:7]
	v_mfma_f32_16x16x32_bf16 v[4:7], v[192:195], v[232:235], v[4:7]
	v_mfma_f32_16x16x32_bf16 v[8:11], v[184:187], v[232:235], v[8:11]
	v_mfma_f32_16x16x32_bf16 v[8:11], v[180:183], v[228:231], v[8:11]
	s_barrier
	s_add_i32 s52, 0, 0x18000
	v_add_u32_e32 v145, s52, v142
	s_add_i32 s53, 0, 0x1c000
	ds_read_b128 v[146:149], v145
	ds_read_b128 v[150:153], v145 offset:1024
	ds_read_b128 v[172:175], v145 offset:2048
	ds_read_b128 v[176:179], v145 offset:3072
	v_add_u32_e32 v145, s53, v142
	ds_read_b128 v[180:183], v145
	ds_read_b128 v[184:187], v145 offset:1024
	ds_read_b128 v[188:191], v145 offset:2048
	ds_read_b128 v[192:195], v145 offset:3072
	s_add_u32 s54, s54, 0x80000
	s_addc_u32 s55, s55, 0
	s_mov_b32 m0, s59
	ds_read_b128 v[196:199], v144 offset:32768
	ds_read_b128 v[200:203], v144 offset:33792
	ds_read_b128 v[204:207], v144 offset:34816
	ds_read_b128 v[208:211], v144 offset:35840
	ds_read_b128 v[212:215], v144 offset:36864
	ds_read_b128 v[216:219], v144 offset:37888
	ds_read_b128 v[228:231], v144 offset:38912
	ds_read_b128 v[232:235], v144 offset:39936
	global_load_lds_dwordx4 v136, s[54:55]
	s_mov_b32 m0, s60
	s_nop 0
	global_load_lds_dwordx4 v132, s[54:55]
	s_waitcnt vmcnt(8)
	s_waitcnt lgkmcnt(0)
	s_barrier
	v_mfma_f32_16x16x32_bf16 v[128:131], v[146:149], v[196:199], v[128:131]
	v_mfma_f32_16x16x32_bf16 v[128:131], v[150:153], v[200:203], v[128:131]
	v_mfma_f32_16x16x32_bf16 v[124:127], v[176:179], v[200:203], v[124:127]
	v_mfma_f32_16x16x32_bf16 v[124:127], v[172:175], v[196:199], v[124:127]
	v_mfma_f32_16x16x32_bf16 v[108:111], v[172:175], v[204:207], v[108:111]
	v_mfma_f32_16x16x32_bf16 v[108:111], v[176:179], v[208:211], v[108:111]
	v_mfma_f32_16x16x32_bf16 v[112:115], v[150:153], v[208:211], v[112:115]
	v_mfma_f32_16x16x32_bf16 v[112:115], v[146:149], v[204:207], v[112:115]
	v_mfma_f32_16x16x32_bf16 v[96:99], v[146:149], v[212:215], v[96:99]
	v_mfma_f32_16x16x32_bf16 v[96:99], v[150:153], v[216:219], v[96:99]
	v_mfma_f32_16x16x32_bf16 v[92:95], v[176:179], v[216:219], v[92:95]
	v_mfma_f32_16x16x32_bf16 v[92:95], v[172:175], v[212:215], v[92:95]
	v_mfma_f32_16x16x32_bf16 v[76:79], v[172:175], v[228:231], v[76:79]
	v_mfma_f32_16x16x32_bf16 v[76:79], v[176:179], v[232:235], v[76:79]
	v_mfma_f32_16x16x32_bf16 v[80:83], v[150:153], v[232:235], v[80:83]
	v_mfma_f32_16x16x32_bf16 v[80:83], v[146:149], v[228:231], v[80:83]
	v_mfma_f32_16x16x32_bf16 v[120:123], v[180:183], v[196:199], v[120:123]
	v_mfma_f32_16x16x32_bf16 v[120:123], v[184:187], v[200:203], v[120:123]
	v_mfma_f32_16x16x32_bf16 v[116:119], v[192:195], v[200:203], v[116:119]
	v_mfma_f32_16x16x32_bf16 v[116:119], v[188:191], v[196:199], v[116:119]
	v_mfma_f32_16x16x32_bf16 v[100:103], v[188:191], v[204:207], v[100:103]
	v_mfma_f32_16x16x32_bf16 v[100:103], v[192:195], v[208:211], v[100:103]
	v_mfma_f32_16x16x32_bf16 v[104:107], v[184:187], v[208:211], v[104:107]
	v_mfma_f32_16x16x32_bf16 v[104:107], v[180:183], v[204:207], v[104:107]
	v_mfma_f32_16x16x32_bf16 v[88:91], v[180:183], v[212:215], v[88:91]
	v_mfma_f32_16x16x32_bf16 v[88:91], v[184:187], v[216:219], v[88:91]
	v_mfma_f32_16x16x32_bf16 v[84:87], v[192:195], v[216:219], v[84:87]
	v_mfma_f32_16x16x32_bf16 v[84:87], v[188:191], v[212:215], v[84:87]
	v_mfma_f32_16x16x32_bf16 v[68:71], v[188:191], v[228:231], v[68:71]
	v_mfma_f32_16x16x32_bf16 v[68:71], v[192:195], v[232:235], v[68:71]
	v_mfma_f32_16x16x32_bf16 v[72:75], v[184:187], v[232:235], v[72:75]
	v_mfma_f32_16x16x32_bf16 v[72:75], v[180:183], v[228:231], v[72:75]
	s_barrier
	s_add_u32 s54, s34, 0x160000
	s_addc_u32 s55, s35, 0
	s_add_i32 s52, s52, s19
	s_mov_b32 m0, s52
	ds_read_b128 v[196:199], v144 offset:49152
	ds_read_b128 v[200:203], v144 offset:50176
	ds_read_b128 v[204:207], v144 offset:51200
	ds_read_b128 v[208:211], v144 offset:52224
	ds_read_b128 v[212:215], v144 offset:53248
	ds_read_b128 v[216:219], v144 offset:54272
	ds_read_b128 v[228:231], v144 offset:55296
	ds_read_b128 v[232:235], v144 offset:56320
	global_load_lds_dwordx4 v134, s[54:55]
	s_add_i32 m0, s52, 0x2000
	s_add_u32 s34, s34, 0x164000
	s_addc_u32 s35, s35, 0
	s_add_i32 s52, s53, s19
	global_load_lds_dwordx4 v0, s[54:55]
	s_mov_b32 m0, s52
	s_nop 0
	global_load_lds_dwordx4 v134, s[34:35]
	s_add_i32 m0, s52, 0x2000
	s_nop 0
	global_load_lds_dwordx4 v0, s[34:35]
	s_mov_b32 m0, s61
	s_nop 0
	global_load_lds_dwordx4 v136, s[100:101]
	s_mov_b32 m0, s62
	s_nop 0
	global_load_lds_dwordx4 v132, s[100:101]
	s_waitcnt vmcnt(8)
	s_waitcnt lgkmcnt(0)
	s_barrier
	v_mfma_f32_16x16x32_bf16 v[64:67], v[146:149], v[196:199], v[64:67]
	v_mfma_f32_16x16x32_bf16 v[64:67], v[150:153], v[200:203], v[64:67]
	v_mfma_f32_16x16x32_bf16 v[60:63], v[176:179], v[200:203], v[60:63]
	v_mfma_f32_16x16x32_bf16 v[60:63], v[172:175], v[196:199], v[60:63]
	v_mfma_f32_16x16x32_bf16 v[44:47], v[172:175], v[204:207], v[44:47]
	v_mfma_f32_16x16x32_bf16 v[44:47], v[176:179], v[208:211], v[44:47]
	v_mfma_f32_16x16x32_bf16 v[48:51], v[150:153], v[208:211], v[48:51]
	v_mfma_f32_16x16x32_bf16 v[48:51], v[146:149], v[204:207], v[48:51]
	v_mfma_f32_16x16x32_bf16 v[32:35], v[146:149], v[212:215], v[32:35]
	v_mfma_f32_16x16x32_bf16 v[32:35], v[150:153], v[216:219], v[32:35]
	v_mfma_f32_16x16x32_bf16 v[28:31], v[176:179], v[216:219], v[28:31]
	v_mfma_f32_16x16x32_bf16 v[28:31], v[172:175], v[212:215], v[28:31]
	v_mfma_f32_16x16x32_bf16 v[12:15], v[172:175], v[228:231], v[12:15]
	v_mfma_f32_16x16x32_bf16 v[12:15], v[176:179], v[232:235], v[12:15]
	v_mfma_f32_16x16x32_bf16 v[16:19], v[150:153], v[232:235], v[16:19]
	v_mfma_f32_16x16x32_bf16 v[16:19], v[146:149], v[228:231], v[16:19]
	v_mfma_f32_16x16x32_bf16 v[56:59], v[180:183], v[196:199], v[56:59]
	v_mfma_f32_16x16x32_bf16 v[56:59], v[184:187], v[200:203], v[56:59]
	v_mfma_f32_16x16x32_bf16 v[52:55], v[192:195], v[200:203], v[52:55]
	v_mfma_f32_16x16x32_bf16 v[52:55], v[188:191], v[196:199], v[52:55]
	v_mfma_f32_16x16x32_bf16 v[36:39], v[188:191], v[204:207], v[36:39]
	v_mfma_f32_16x16x32_bf16 v[36:39], v[192:195], v[208:211], v[36:39]
	v_mfma_f32_16x16x32_bf16 v[40:43], v[184:187], v[208:211], v[40:43]
	v_mfma_f32_16x16x32_bf16 v[40:43], v[180:183], v[204:207], v[40:43]
	v_mfma_f32_16x16x32_bf16 v[24:27], v[180:183], v[212:215], v[24:27]
	v_mfma_f32_16x16x32_bf16 v[24:27], v[184:187], v[216:219], v[24:27]
	v_mfma_f32_16x16x32_bf16 v[20:23], v[192:195], v[216:219], v[20:23]
	v_mfma_f32_16x16x32_bf16 v[20:23], v[188:191], v[212:215], v[20:23]
	v_mfma_f32_16x16x32_bf16 v[4:7], v[188:191], v[228:231], v[4:7]
	v_mfma_f32_16x16x32_bf16 v[4:7], v[192:195], v[232:235], v[4:7]
	v_mfma_f32_16x16x32_bf16 v[8:11], v[184:187], v[232:235], v[8:11]
	v_mfma_f32_16x16x32_bf16 v[8:11], v[180:183], v[228:231], v[8:11]
	s_barrier
	s_add_i32 s77, s77, 2
	s_add_u32 s71, s71, 0x2c0000
	s_addc_u32 s76, s76, 0
	s_add_u32 s50, s50, 0x100
	s_addc_u32 s51, s51, 0
	s_cmp_gt_u32 s77, 29
	s_cbranch_scc0 .LBB0_169
	s_setprio 0
	s_and_b64 vcc, exec, s[28:29]
	s_cbranch_vccz .LBB0_172
	s_barrier

.Lprio_skip_2:
.LBB0_243:
	s_add_u32 s34, s44, 0xfff80080
	s_addc_u32 s35, s45, -1
	s_add_i32 s52, 0, 0x10000
	s_cmp_eq_u32 vcc_hi, 28
	s_cselect_b32 s47, s36, s35
	s_cselect_b32 s46, s37, s34
	s_cselect_b32 s35, s55, vcc_lo
	s_cselect_b32 s34, s57, s63
	s_add_i32 s68, 0, 0x14000
	v_add_u32_e32 v144, s52, v155
	v_add_u32_e32 v180, s68, v155
	ds_read_b128 v[132:135], v144
	ds_read_b128 v[136:139], v144 offset:1024
	ds_read_b128 v[140:143], v144 offset:2048
	ds_read_b128 v[144:147], v144 offset:3072
	ds_read_b128 v[176:179], v180
	ds_read_b128 v[182:185], v180 offset:1024
	ds_read_b128 v[186:189], v180 offset:2048
	ds_read_b128 v[190:193], v180 offset:3072
	s_add_i32 m0, s69, 0xc000
	ds_read_b128 v[194:197], v181
	ds_read_b128 v[198:201], v181 offset:1024
	ds_read_b128 v[202:205], v181 offset:2048
	ds_read_b128 v[206:209], v181 offset:3072
	ds_read_b128 v[210:213], v181 offset:4096
	ds_read_b128 v[214:217], v181 offset:5120
	ds_read_b128 v[228:231], v181 offset:6144
	ds_read_b128 v[232:235], v181 offset:7168
	global_load_lds_dwordx4 v172, s[44:45]
	s_add_i32 m0, s69, 0xe000
	s_nop 0
	global_load_lds_dwordx4 v174, s[44:45]
	s_waitcnt vmcnt(8)
	s_waitcnt lgkmcnt(0)
	s_barrier
	v_mfma_f32_16x16x32_bf16 v[128:131], v[132:135], v[194:197], v[128:131]
	v_mfma_f32_16x16x32_bf16 v[128:131], v[136:139], v[198:201], v[128:131]
	v_mfma_f32_16x16x32_bf16 v[124:127], v[144:147], v[198:201], v[124:127]
	v_mfma_f32_16x16x32_bf16 v[124:127], v[140:143], v[194:197], v[124:127]
	v_mfma_f32_16x16x32_bf16 v[108:111], v[140:143], v[202:205], v[108:111]
	v_mfma_f32_16x16x32_bf16 v[108:111], v[144:147], v[206:209], v[108:111]
	v_mfma_f32_16x16x32_bf16 v[112:115], v[136:139], v[206:209], v[112:115]
	v_mfma_f32_16x16x32_bf16 v[112:115], v[132:135], v[202:205], v[112:115]
	v_mfma_f32_16x16x32_bf16 v[96:99], v[132:135], v[210:213], v[96:99]
	v_mfma_f32_16x16x32_bf16 v[96:99], v[136:139], v[214:217], v[96:99]
	v_mfma_f32_16x16x32_bf16 v[92:95], v[144:147], v[214:217], v[92:95]
	v_mfma_f32_16x16x32_bf16 v[92:95], v[140:143], v[210:213], v[92:95]
	v_mfma_f32_16x16x32_bf16 v[76:79], v[140:143], v[228:231], v[76:79]
	v_mfma_f32_16x16x32_bf16 v[76:79], v[144:147], v[232:235], v[76:79]
	v_mfma_f32_16x16x32_bf16 v[80:83], v[136:139], v[232:235], v[80:83]
	v_mfma_f32_16x16x32_bf16 v[80:83], v[132:135], v[228:231], v[80:83]
	v_mfma_f32_16x16x32_bf16 v[120:123], v[176:179], v[194:197], v[120:123]
	v_mfma_f32_16x16x32_bf16 v[120:123], v[182:185], v[198:201], v[120:123]
	v_mfma_f32_16x16x32_bf16 v[116:119], v[190:193], v[198:201], v[116:119]
	v_mfma_f32_16x16x32_bf16 v[116:119], v[186:189], v[194:197], v[116:119]
	v_mfma_f32_16x16x32_bf16 v[100:103], v[186:189], v[202:205], v[100:103]
	v_mfma_f32_16x16x32_bf16 v[100:103], v[190:193], v[206:209], v[100:103]
	v_mfma_f32_16x16x32_bf16 v[104:107], v[182:185], v[206:209], v[104:107]
	v_mfma_f32_16x16x32_bf16 v[104:107], v[176:179], v[202:205], v[104:107]
	v_mfma_f32_16x16x32_bf16 v[88:91], v[176:179], v[210:213], v[88:91]
	v_mfma_f32_16x16x32_bf16 v[88:91], v[182:185], v[214:217], v[88:91]
	v_mfma_f32_16x16x32_bf16 v[84:87], v[190:193], v[214:217], v[84:87]
	v_mfma_f32_16x16x32_bf16 v[84:87], v[186:189], v[210:213], v[84:87]
	v_mfma_f32_16x16x32_bf16 v[68:71], v[186:189], v[228:231], v[68:71]
	v_mfma_f32_16x16x32_bf16 v[68:71], v[190:193], v[232:235], v[68:71]
	v_mfma_f32_16x16x32_bf16 v[72:75], v[182:185], v[232:235], v[72:75]
	v_mfma_f32_16x16x32_bf16 v[72:75], v[176:179], v[228:231], v[72:75]
	s_barrier
	s_add_u32 s100, s46, s14
	s_addc_u32 s101, s47, s15
	s_add_i32 s52, s52, s2
	s_mov_b32 m0, s52
	ds_read_b128 v[194:197], v181 offset:16384
	ds_read_b128 v[198:201], v181 offset:17408
	ds_read_b128 v[202:205], v181 offset:18432
	ds_read_b128 v[206:209], v181 offset:19456
	ds_read_b128 v[210:213], v181 offset:20480
	ds_read_b128 v[214:217], v181 offset:21504
	ds_read_b128 v[228:231], v181 offset:22528
	ds_read_b128 v[232:235], v181 offset:23552
	global_load_lds_dwordx4 v150, s[34:35]
	s_add_i32 m0, s52, 0x2000
	s_add_u32 s52, s34, 0x4000
	s_addc_u32 s53, s35, 0
	s_add_i32 s68, s68, s2
	global_load_lds_dwordx4 v0, s[34:35]
	s_mov_b32 m0, s68
	s_nop 0
	global_load_lds_dwordx4 v150, s[52:53]
	s_add_i32 m0, s68, 0x2000
	s_nop 0
	global_load_lds_dwordx4 v0, s[52:53]
	s_mov_b32 m0, s69
	s_nop 0
	global_load_lds_dwordx4 v152, s[46:47]
	s_mov_b32 m0, s71
	s_nop 0
	global_load_lds_dwordx4 v148, s[46:47]
	s_waitcnt vmcnt(8)
	s_waitcnt lgkmcnt(0)
	s_barrier
	v_mfma_f32_16x16x32_bf16 v[64:67], v[132:135], v[194:197], v[64:67]
	v_mfma_f32_16x16x32_bf16 v[64:67], v[136:139], v[198:201], v[64:67]
	v_mfma_f32_16x16x32_bf16 v[60:63], v[144:147], v[198:201], v[60:63]
	v_mfma_f32_16x16x32_bf16 v[60:63], v[140:143], v[194:197], v[60:63]
	v_mfma_f32_16x16x32_bf16 v[44:47], v[140:143], v[202:205], v[44:47]
	v_mfma_f32_16x16x32_bf16 v[44:47], v[144:147], v[206:209], v[44:47]
	v_mfma_f32_16x16x32_bf16 v[48:51], v[136:139], v[206:209], v[48:51]
	v_mfma_f32_16x16x32_bf16 v[48:51], v[132:135], v[202:205], v[48:51]
	v_mfma_f32_16x16x32_bf16 v[32:35], v[132:135], v[210:213], v[32:35]
	v_mfma_f32_16x16x32_bf16 v[32:35], v[136:139], v[214:217], v[32:35]
	v_mfma_f32_16x16x32_bf16 v[28:31], v[144:147], v[214:217], v[28:31]
	v_mfma_f32_16x16x32_bf16 v[28:31], v[140:143], v[210:213], v[28:31]
	v_mfma_f32_16x16x32_bf16 v[12:15], v[140:143], v[228:231], v[12:15]
	v_mfma_f32_16x16x32_bf16 v[12:15], v[144:147], v[232:235], v[12:15]
	v_mfma_f32_16x16x32_bf16 v[16:19], v[136:139], v[232:235], v[16:19]
	v_mfma_f32_16x16x32_bf16 v[16:19], v[132:135], v[228:231], v[16:19]
	v_mfma_f32_16x16x32_bf16 v[56:59], v[176:179], v[194:197], v[56:59]
	v_mfma_f32_16x16x32_bf16 v[56:59], v[182:185], v[198:201], v[56:59]
	v_mfma_f32_16x16x32_bf16 v[52:55], v[190:193], v[198:201], v[52:55]
	v_mfma_f32_16x16x32_bf16 v[52:55], v[186:189], v[194:197], v[52:55]
	v_mfma_f32_16x16x32_bf16 v[36:39], v[186:189], v[202:205], v[36:39]
	v_mfma_f32_16x16x32_bf16 v[36:39], v[190:193], v[206:209], v[36:39]
	v_mfma_f32_16x16x32_bf16 v[40:43], v[182:185], v[206:209], v[40:43]
	v_mfma_f32_16x16x32_bf16 v[40:43], v[176:179], v[202:205], v[40:43]
	v_mfma_f32_16x16x32_bf16 v[24:27], v[176:179], v[210:213], v[24:27]
	v_mfma_f32_16x16x32_bf16 v[24:27], v[182:185], v[214:217], v[24:27]
	v_mfma_f32_16x16x32_bf16 v[20:23], v[190:193], v[214:217], v[20:23]
	v_mfma_f32_16x16x32_bf16 v[20:23], v[186:189], v[210:213], v[20:23]
	v_mfma_f32_16x16x32_bf16 v[4:7], v[186:189], v[228:231], v[4:7]
	v_mfma_f32_16x16x32_bf16 v[4:7], v[190:193], v[232:235], v[4:7]
	v_mfma_f32_16x16x32_bf16 v[8:11], v[182:185], v[232:235], v[8:11]
	v_mfma_f32_16x16x32_bf16 v[8:11], v[176:179], v[228:231], v[8:11]
	s_barrier
	s_add_i32 s52, 0, 0x18000
	s_add_i32 s53, 0, 0x1c000
	v_add_u32_e32 v144, s52, v155
	v_add_u32_e32 v180, s53, v155
	ds_read_b128 v[132:135], v144
	ds_read_b128 v[136:139], v144 offset:1024
	ds_read_b128 v[140:143], v144 offset:2048
	ds_read_b128 v[144:147], v144 offset:3072
	ds_read_b128 v[176:179], v180
	ds_read_b128 v[182:185], v180 offset:1024
	ds_read_b128 v[186:189], v180 offset:2048
	ds_read_b128 v[190:193], v180 offset:3072
	s_add_u32 s46, s46, 0x80000
	s_addc_u32 s47, s47, 0
	s_mov_b32 m0, s88
	ds_read_b128 v[194:197], v181 offset:32768
	ds_read_b128 v[198:201], v181 offset:33792
	ds_read_b128 v[202:205], v181 offset:34816
	ds_read_b128 v[206:209], v181 offset:35840
	ds_read_b128 v[210:213], v181 offset:36864
	ds_read_b128 v[214:217], v181 offset:37888
	ds_read_b128 v[228:231], v181 offset:38912
	ds_read_b128 v[232:235], v181 offset:39936
	global_load_lds_dwordx4 v152, s[46:47]
	s_mov_b32 m0, s96
	s_nop 0
	global_load_lds_dwordx4 v148, s[46:47]
	s_waitcnt vmcnt(8)
	s_waitcnt lgkmcnt(0)
	s_barrier
	v_mfma_f32_16x16x32_bf16 v[128:131], v[132:135], v[194:197], v[128:131]
	v_mfma_f32_16x16x32_bf16 v[128:131], v[136:139], v[198:201], v[128:131]
	v_mfma_f32_16x16x32_bf16 v[124:127], v[144:147], v[198:201], v[124:127]
	v_mfma_f32_16x16x32_bf16 v[124:127], v[140:143], v[194:197], v[124:127]
	v_mfma_f32_16x16x32_bf16 v[108:111], v[140:143], v[202:205], v[108:111]
	v_mfma_f32_16x16x32_bf16 v[108:111], v[144:147], v[206:209], v[108:111]
	v_mfma_f32_16x16x32_bf16 v[112:115], v[136:139], v[206:209], v[112:115]
	v_mfma_f32_16x16x32_bf16 v[112:115], v[132:135], v[202:205], v[112:115]
	v_mfma_f32_16x16x32_bf16 v[96:99], v[132:135], v[210:213], v[96:99]
	v_mfma_f32_16x16x32_bf16 v[96:99], v[136:139], v[214:217], v[96:99]
	v_mfma_f32_16x16x32_bf16 v[92:95], v[144:147], v[214:217], v[92:95]
	v_mfma_f32_16x16x32_bf16 v[92:95], v[140:143], v[210:213], v[92:95]
	v_mfma_f32_16x16x32_bf16 v[76:79], v[140:143], v[228:231], v[76:79]
	v_mfma_f32_16x16x32_bf16 v[76:79], v[144:147], v[232:235], v[76:79]
	v_mfma_f32_16x16x32_bf16 v[80:83], v[136:139], v[232:235], v[80:83]
	v_mfma_f32_16x16x32_bf16 v[80:83], v[132:135], v[228:231], v[80:83]
	v_mfma_f32_16x16x32_bf16 v[120:123], v[176:179], v[194:197], v[120:123]
	v_mfma_f32_16x16x32_bf16 v[120:123], v[182:185], v[198:201], v[120:123]
	v_mfma_f32_16x16x32_bf16 v[116:119], v[190:193], v[198:201], v[116:119]
	v_mfma_f32_16x16x32_bf16 v[116:119], v[186:189], v[194:197], v[116:119]
	v_mfma_f32_16x16x32_bf16 v[100:103], v[186:189], v[202:205], v[100:103]
	v_mfma_f32_16x16x32_bf16 v[100:103], v[190:193], v[206:209], v[100:103]
	v_mfma_f32_16x16x32_bf16 v[104:107], v[182:185], v[206:209], v[104:107]
	v_mfma_f32_16x16x32_bf16 v[104:107], v[176:179], v[202:205], v[104:107]
	v_mfma_f32_16x16x32_bf16 v[88:91], v[176:179], v[210:213], v[88:91]
	v_mfma_f32_16x16x32_bf16 v[88:91], v[182:185], v[214:217], v[88:91]
	v_mfma_f32_16x16x32_bf16 v[84:87], v[190:193], v[214:217], v[84:87]
	v_mfma_f32_16x16x32_bf16 v[84:87], v[186:189], v[210:213], v[84:87]
	v_mfma_f32_16x16x32_bf16 v[68:71], v[186:189], v[228:231], v[68:71]
	v_mfma_f32_16x16x32_bf16 v[68:71], v[190:193], v[232:235], v[68:71]
	v_mfma_f32_16x16x32_bf16 v[72:75], v[182:185], v[232:235], v[72:75]
	v_mfma_f32_16x16x32_bf16 v[72:75], v[176:179], v[228:231], v[72:75]
	s_barrier
	s_add_u32 s46, s34, 0x70000
	s_addc_u32 s47, s35, 0
	s_add_i32 s52, s52, s2
	s_mov_b32 m0, s52
	ds_read_b128 v[194:197], v181 offset:49152
	ds_read_b128 v[198:201], v181 offset:50176
	ds_read_b128 v[202:205], v181 offset:51200
	ds_read_b128 v[206:209], v181 offset:52224
	ds_read_b128 v[210:213], v181 offset:53248
	ds_read_b128 v[214:217], v181 offset:54272
	ds_read_b128 v[228:231], v181 offset:55296
	ds_read_b128 v[232:235], v181 offset:56320
	global_load_lds_dwordx4 v150, s[46:47]
	s_add_i32 m0, s52, 0x2000
	s_add_u32 s34, s34, 0x74000
	global_load_lds_dwordx4 v0, s[46:47]
	s_addc_u32 s35, s35, 0
	s_add_i32 s46, s53, s2
	s_mov_b32 m0, s46
	s_nop 0
	global_load_lds_dwordx4 v150, s[34:35]
	s_add_i32 m0, s46, 0x2000
	s_nop 0
	global_load_lds_dwordx4 v0, s[34:35]
	s_mov_b32 m0, s97
	s_nop 0
	global_load_lds_dwordx4 v152, s[100:101]
	s_mov_b32 m0, s76
	s_nop 0
	global_load_lds_dwordx4 v148, s[100:101]
	s_waitcnt vmcnt(8)
	s_waitcnt lgkmcnt(0)
	s_barrier
	v_mfma_f32_16x16x32_bf16 v[64:67], v[132:135], v[194:197], v[64:67]
	v_mfma_f32_16x16x32_bf16 v[64:67], v[136:139], v[198:201], v[64:67]
	v_mfma_f32_16x16x32_bf16 v[60:63], v[144:147], v[198:201], v[60:63]
	v_mfma_f32_16x16x32_bf16 v[60:63], v[140:143], v[194:197], v[60:63]
	v_mfma_f32_16x16x32_bf16 v[44:47], v[140:143], v[202:205], v[44:47]
	v_mfma_f32_16x16x32_bf16 v[44:47], v[144:147], v[206:209], v[44:47]
	v_mfma_f32_16x16x32_bf16 v[48:51], v[136:139], v[206:209], v[48:51]
	v_mfma_f32_16x16x32_bf16 v[48:51], v[132:135], v[202:205], v[48:51]
	v_mfma_f32_16x16x32_bf16 v[32:35], v[132:135], v[210:213], v[32:35]
	v_mfma_f32_16x16x32_bf16 v[32:35], v[136:139], v[214:217], v[32:35]
	v_mfma_f32_16x16x32_bf16 v[28:31], v[144:147], v[214:217], v[28:31]
	v_mfma_f32_16x16x32_bf16 v[28:31], v[140:143], v[210:213], v[28:31]
	v_mfma_f32_16x16x32_bf16 v[12:15], v[140:143], v[228:231], v[12:15]
	v_mfma_f32_16x16x32_bf16 v[12:15], v[144:147], v[232:235], v[12:15]
	v_mfma_f32_16x16x32_bf16 v[16:19], v[136:139], v[232:235], v[16:19]
	v_mfma_f32_16x16x32_bf16 v[16:19], v[132:135], v[228:231], v[16:19]
	v_mfma_f32_16x16x32_bf16 v[56:59], v[176:179], v[194:197], v[56:59]
	v_mfma_f32_16x16x32_bf16 v[56:59], v[182:185], v[198:201], v[56:59]
	v_mfma_f32_16x16x32_bf16 v[52:55], v[190:193], v[198:201], v[52:55]
	v_mfma_f32_16x16x32_bf16 v[52:55], v[186:189], v[194:197], v[52:55]
	v_mfma_f32_16x16x32_bf16 v[36:39], v[186:189], v[202:205], v[36:39]
	v_mfma_f32_16x16x32_bf16 v[36:39], v[190:193], v[206:209], v[36:39]
	v_mfma_f32_16x16x32_bf16 v[40:43], v[182:185], v[206:209], v[40:43]
	v_mfma_f32_16x16x32_bf16 v[40:43], v[176:179], v[202:205], v[40:43]
	v_mfma_f32_16x16x32_bf16 v[24:27], v[176:179], v[210:213], v[24:27]
	v_mfma_f32_16x16x32_bf16 v[24:27], v[182:185], v[214:217], v[24:27]
	v_mfma_f32_16x16x32_bf16 v[20:23], v[190:193], v[214:217], v[20:23]
	v_mfma_f32_16x16x32_bf16 v[20:23], v[186:189], v[210:213], v[20:23]
	v_mfma_f32_16x16x32_bf16 v[4:7], v[186:189], v[228:231], v[4:7]
	v_mfma_f32_16x16x32_bf16 v[4:7], v[190:193], v[232:235], v[4:7]
	v_mfma_f32_16x16x32_bf16 v[8:11], v[182:185], v[232:235], v[8:11]
	v_mfma_f32_16x16x32_bf16 v[8:11], v[176:179], v[228:231], v[8:11]
	s_barrier
	s_add_i32 vcc_hi, vcc_hi, 2
	s_add_u32 s63, s63, 0xe0000
	s_addc_u32 vcc_lo, vcc_lo, 0
	s_add_u32 s44, s44, 0x100
	s_addc_u32 s45, s45, 0
	s_cmp_gt_u32 vcc_hi, 29
	s_cbranch_scc0 .LBB0_243
	s_setprio 0
	s_and_b64 vcc, exec, s[28:29]
	s_cbranch_vccz .LBB0_246
	s_barrier

.Lprio_skip_3:
.LBB0_559:
	s_add_i32 vcc_lo, s34, 2
	s_add_u32 s35, s42, 0x80
	s_addc_u32 s52, s43, 0
	s_add_i32 s53, 0, 0x10000
	s_cmp_eq_u32 s77, s34
	s_cselect_b32 s57, s51, s52
	s_cselect_b32 s56, s50, s35
	s_cselect_b32 s35, s36, s97
	s_cselect_b32 s34, s37, s49
	s_add_i32 s68, 0, 0x14000
	v_add_u32_e32 v136, s53, v200
	v_add_u32_e32 v186, s68, v200
	ds_read_b128 v[116:119], v136
	ds_read_b128 v[120:123], v136 offset:1024
	ds_read_b128 v[124:127], v136 offset:2048
	ds_read_b128 v[136:139], v136 offset:3072
	ds_read_b128 v[148:151], v186
	ds_read_b128 v[152:155], v186 offset:1024
	ds_read_b128 v[182:185], v186 offset:2048
	ds_read_b128 v[186:189], v186 offset:3072
	s_add_i32 m0, s59, 0xc000
	ds_read_b128 v[190:193], v202
	ds_read_b128 v[194:197], v202 offset:1024
	ds_read_b128 v[204:207], v202 offset:2048
	ds_read_b128 v[208:211], v202 offset:3072
	ds_read_b128 v[212:215], v202 offset:4096
	ds_read_b128 v[216:219], v202 offset:5120
	ds_read_b128 v[228:231], v202 offset:6144
	ds_read_b128 v[232:235], v202 offset:7168
	global_load_lds_dwordx4 v178, s[42:43]
	s_add_i32 m0, s59, 0xe000
	s_nop 0
	global_load_lds_dwordx4 v180, s[42:43]
	s_waitcnt vmcnt(8)
	s_waitcnt lgkmcnt(0)
	s_barrier
	v_mfma_f32_16x16x32_bf16 v[144:147], v[116:119], v[190:193], v[144:147]
	v_mfma_f32_16x16x32_bf16 v[144:147], v[120:123], v[194:197], v[144:147]
	v_mfma_f32_16x16x32_bf16 v[140:143], v[136:139], v[194:197], v[140:143]
	v_mfma_f32_16x16x32_bf16 v[140:143], v[124:127], v[190:193], v[140:143]
	v_mfma_f32_16x16x32_bf16 v[108:111], v[124:127], v[204:207], v[108:111]
	v_mfma_f32_16x16x32_bf16 v[108:111], v[136:139], v[208:211], v[108:111]
	v_mfma_f32_16x16x32_bf16 v[112:115], v[120:123], v[208:211], v[112:115]
	v_mfma_f32_16x16x32_bf16 v[112:115], v[116:119], v[204:207], v[112:115]
	v_mfma_f32_16x16x32_bf16 v[96:99], v[116:119], v[212:215], v[96:99]
	v_mfma_f32_16x16x32_bf16 v[96:99], v[120:123], v[216:219], v[96:99]
	v_mfma_f32_16x16x32_bf16 v[92:95], v[136:139], v[216:219], v[92:95]
	v_mfma_f32_16x16x32_bf16 v[92:95], v[124:127], v[212:215], v[92:95]
	v_mfma_f32_16x16x32_bf16 v[76:79], v[124:127], v[228:231], v[76:79]
	v_mfma_f32_16x16x32_bf16 v[76:79], v[136:139], v[232:235], v[76:79]
	v_mfma_f32_16x16x32_bf16 v[80:83], v[120:123], v[232:235], v[80:83]
	v_mfma_f32_16x16x32_bf16 v[80:83], v[116:119], v[228:231], v[80:83]
	v_mfma_f32_16x16x32_bf16 v[132:135], v[148:151], v[190:193], v[132:135]
	v_mfma_f32_16x16x32_bf16 v[132:135], v[152:155], v[194:197], v[132:135]
	v_mfma_f32_16x16x32_bf16 v[128:131], v[186:189], v[194:197], v[128:131]
	v_mfma_f32_16x16x32_bf16 v[128:131], v[182:185], v[190:193], v[128:131]
	v_mfma_f32_16x16x32_bf16 v[100:103], v[182:185], v[204:207], v[100:103]
	v_mfma_f32_16x16x32_bf16 v[100:103], v[186:189], v[208:211], v[100:103]
	v_mfma_f32_16x16x32_bf16 v[104:107], v[152:155], v[208:211], v[104:107]
	v_mfma_f32_16x16x32_bf16 v[104:107], v[148:151], v[204:207], v[104:107]
	v_mfma_f32_16x16x32_bf16 v[88:91], v[148:151], v[212:215], v[88:91]
	v_mfma_f32_16x16x32_bf16 v[88:91], v[152:155], v[216:219], v[88:91]
	v_mfma_f32_16x16x32_bf16 v[84:87], v[186:189], v[216:219], v[84:87]
	v_mfma_f32_16x16x32_bf16 v[84:87], v[182:185], v[212:215], v[84:87]
	v_mfma_f32_16x16x32_bf16 v[68:71], v[182:185], v[228:231], v[68:71]
	v_mfma_f32_16x16x32_bf16 v[68:71], v[186:189], v[232:235], v[68:71]
	v_mfma_f32_16x16x32_bf16 v[72:75], v[152:155], v[232:235], v[72:75]
	v_mfma_f32_16x16x32_bf16 v[72:75], v[148:151], v[228:231], v[72:75]
	s_barrier
	s_add_u32 s100, s56, s14
	s_addc_u32 s101, s57, s15
	s_add_i32 s52, s53, s58
	s_mov_b32 m0, s52
	ds_read_b128 v[190:193], v202 offset:16384
	ds_read_b128 v[194:197], v202 offset:17408
	ds_read_b128 v[204:207], v202 offset:18432
	ds_read_b128 v[208:211], v202 offset:19456
	ds_read_b128 v[212:215], v202 offset:20480
	ds_read_b128 v[216:219], v202 offset:21504
	ds_read_b128 v[228:231], v202 offset:22528
	ds_read_b128 v[232:235], v202 offset:23552
	global_load_lds_dwordx4 v174, s[34:35]
	s_add_i32 m0, s52, 0x2000
	s_add_u32 s52, s34, 0x4000
	s_addc_u32 s53, s35, 0
	s_add_i32 s68, s68, s58
	global_load_lds_dwordx4 v0, s[34:35]
	s_mov_b32 m0, s68
	s_nop 0
	global_load_lds_dwordx4 v174, s[52:53]
	s_add_i32 m0, s68, 0x2000
	s_nop 0
	global_load_lds_dwordx4 v0, s[52:53]
	s_mov_b32 m0, s59
	s_nop 0
	global_load_lds_dwordx4 v176, s[56:57]
	s_mov_b32 m0, s60
	s_nop 0
	global_load_lds_dwordx4 v172, s[56:57]
	s_waitcnt vmcnt(8)
	s_waitcnt lgkmcnt(0)
	s_barrier
	v_mfma_f32_16x16x32_bf16 v[64:67], v[116:119], v[190:193], v[64:67]
	v_mfma_f32_16x16x32_bf16 v[64:67], v[120:123], v[194:197], v[64:67]
	v_mfma_f32_16x16x32_bf16 v[60:63], v[136:139], v[194:197], v[60:63]
	v_mfma_f32_16x16x32_bf16 v[60:63], v[124:127], v[190:193], v[60:63]
	v_mfma_f32_16x16x32_bf16 v[44:47], v[124:127], v[204:207], v[44:47]
	v_mfma_f32_16x16x32_bf16 v[44:47], v[136:139], v[208:211], v[44:47]
	v_mfma_f32_16x16x32_bf16 v[48:51], v[120:123], v[208:211], v[48:51]
	v_mfma_f32_16x16x32_bf16 v[48:51], v[116:119], v[204:207], v[48:51]
	v_mfma_f32_16x16x32_bf16 v[32:35], v[116:119], v[212:215], v[32:35]
	v_mfma_f32_16x16x32_bf16 v[32:35], v[120:123], v[216:219], v[32:35]
	v_mfma_f32_16x16x32_bf16 v[28:31], v[136:139], v[216:219], v[28:31]
	v_mfma_f32_16x16x32_bf16 v[28:31], v[124:127], v[212:215], v[28:31]
	v_mfma_f32_16x16x32_bf16 v[12:15], v[124:127], v[228:231], v[12:15]
	v_mfma_f32_16x16x32_bf16 v[12:15], v[136:139], v[232:235], v[12:15]
	v_mfma_f32_16x16x32_bf16 v[16:19], v[120:123], v[232:235], v[16:19]
	v_mfma_f32_16x16x32_bf16 v[16:19], v[116:119], v[228:231], v[16:19]
	v_mfma_f32_16x16x32_bf16 v[56:59], v[148:151], v[190:193], v[56:59]
	v_mfma_f32_16x16x32_bf16 v[56:59], v[152:155], v[194:197], v[56:59]
	v_mfma_f32_16x16x32_bf16 v[52:55], v[186:189], v[194:197], v[52:55]
	v_mfma_f32_16x16x32_bf16 v[52:55], v[182:185], v[190:193], v[52:55]
	v_mfma_f32_16x16x32_bf16 v[36:39], v[182:185], v[204:207], v[36:39]
	v_mfma_f32_16x16x32_bf16 v[36:39], v[186:189], v[208:211], v[36:39]
	v_mfma_f32_16x16x32_bf16 v[40:43], v[152:155], v[208:211], v[40:43]
	v_mfma_f32_16x16x32_bf16 v[40:43], v[148:151], v[204:207], v[40:43]
	v_mfma_f32_16x16x32_bf16 v[24:27], v[148:151], v[212:215], v[24:27]
	v_mfma_f32_16x16x32_bf16 v[24:27], v[152:155], v[216:219], v[24:27]
	v_mfma_f32_16x16x32_bf16 v[20:23], v[186:189], v[216:219], v[20:23]
	v_mfma_f32_16x16x32_bf16 v[20:23], v[182:185], v[212:215], v[20:23]
	v_mfma_f32_16x16x32_bf16 v[4:7], v[182:185], v[228:231], v[4:7]
	v_mfma_f32_16x16x32_bf16 v[4:7], v[186:189], v[232:235], v[4:7]
	v_mfma_f32_16x16x32_bf16 v[8:11], v[152:155], v[232:235], v[8:11]
	v_mfma_f32_16x16x32_bf16 v[8:11], v[148:151], v[228:231], v[8:11]
	s_barrier
	s_add_i32 s68, 0, 0x18000
	s_add_i32 vcc_hi, 0, 0x1c000
	v_add_u32_e32 v136, s68, v200
	v_add_u32_e32 v186, vcc_hi, v200
	ds_read_b128 v[116:119], v136
	ds_read_b128 v[120:123], v136 offset:1024
	ds_read_b128 v[124:127], v136 offset:2048
	ds_read_b128 v[136:139], v136 offset:3072
	ds_read_b128 v[148:151], v186
	ds_read_b128 v[152:155], v186 offset:1024
	ds_read_b128 v[182:185], v186 offset:2048
	ds_read_b128 v[186:189], v186 offset:3072
	s_add_u32 s52, s56, s26
	s_addc_u32 s53, s57, 0
	s_mov_b32 m0, s61
	ds_read_b128 v[190:193], v202 offset:32768
	ds_read_b128 v[194:197], v202 offset:33792
	ds_read_b128 v[204:207], v202 offset:34816
	ds_read_b128 v[208:211], v202 offset:35840
	ds_read_b128 v[212:215], v202 offset:36864
	ds_read_b128 v[216:219], v202 offset:37888
	ds_read_b128 v[228:231], v202 offset:38912
	ds_read_b128 v[232:235], v202 offset:39936
	global_load_lds_dwordx4 v176, s[52:53]
	s_mov_b32 m0, s62
	s_nop 0
	global_load_lds_dwordx4 v172, s[52:53]
	s_waitcnt vmcnt(8)
	s_waitcnt lgkmcnt(0)
	s_barrier
	v_mfma_f32_16x16x32_bf16 v[144:147], v[116:119], v[190:193], v[144:147]
	v_mfma_f32_16x16x32_bf16 v[144:147], v[120:123], v[194:197], v[144:147]
	v_mfma_f32_16x16x32_bf16 v[140:143], v[136:139], v[194:197], v[140:143]
	v_mfma_f32_16x16x32_bf16 v[140:143], v[124:127], v[190:193], v[140:143]
	v_mfma_f32_16x16x32_bf16 v[108:111], v[124:127], v[204:207], v[108:111]
	v_mfma_f32_16x16x32_bf16 v[108:111], v[136:139], v[208:211], v[108:111]
	v_mfma_f32_16x16x32_bf16 v[112:115], v[120:123], v[208:211], v[112:115]
	v_mfma_f32_16x16x32_bf16 v[112:115], v[116:119], v[204:207], v[112:115]
	v_mfma_f32_16x16x32_bf16 v[96:99], v[116:119], v[212:215], v[96:99]
	v_mfma_f32_16x16x32_bf16 v[96:99], v[120:123], v[216:219], v[96:99]
	v_mfma_f32_16x16x32_bf16 v[92:95], v[136:139], v[216:219], v[92:95]
	v_mfma_f32_16x16x32_bf16 v[92:95], v[124:127], v[212:215], v[92:95]
	v_mfma_f32_16x16x32_bf16 v[76:79], v[124:127], v[228:231], v[76:79]
	v_mfma_f32_16x16x32_bf16 v[76:79], v[136:139], v[232:235], v[76:79]
	v_mfma_f32_16x16x32_bf16 v[80:83], v[120:123], v[232:235], v[80:83]
	v_mfma_f32_16x16x32_bf16 v[80:83], v[116:119], v[228:231], v[80:83]
	v_mfma_f32_16x16x32_bf16 v[132:135], v[148:151], v[190:193], v[132:135]
	v_mfma_f32_16x16x32_bf16 v[132:135], v[152:155], v[194:197], v[132:135]
	v_mfma_f32_16x16x32_bf16 v[128:131], v[186:189], v[194:197], v[128:131]
	v_mfma_f32_16x16x32_bf16 v[128:131], v[182:185], v[190:193], v[128:131]
	v_mfma_f32_16x16x32_bf16 v[100:103], v[182:185], v[204:207], v[100:103]
	v_mfma_f32_16x16x32_bf16 v[100:103], v[186:189], v[208:211], v[100:103]
	v_mfma_f32_16x16x32_bf16 v[104:107], v[152:155], v[208:211], v[104:107]
	v_mfma_f32_16x16x32_bf16 v[104:107], v[148:151], v[204:207], v[104:107]
	v_mfma_f32_16x16x32_bf16 v[88:91], v[148:151], v[212:215], v[88:91]
	v_mfma_f32_16x16x32_bf16 v[88:91], v[152:155], v[216:219], v[88:91]
	v_mfma_f32_16x16x32_bf16 v[84:87], v[186:189], v[216:219], v[84:87]
	v_mfma_f32_16x16x32_bf16 v[84:87], v[182:185], v[212:215], v[84:87]
	v_mfma_f32_16x16x32_bf16 v[68:71], v[182:185], v[228:231], v[68:71]
	v_mfma_f32_16x16x32_bf16 v[68:71], v[186:189], v[232:235], v[68:71]
	v_mfma_f32_16x16x32_bf16 v[72:75], v[152:155], v[232:235], v[72:75]
	v_mfma_f32_16x16x32_bf16 v[72:75], v[148:151], v[228:231], v[72:75]
	s_barrier
	s_add_u32 s52, s34, 0x40000
	s_addc_u32 s53, s35, 0
	s_add_i32 s56, s68, s58
	s_mov_b32 m0, s56
	ds_read_b128 v[190:193], v202 offset:49152
	ds_read_b128 v[194:197], v202 offset:50176
	ds_read_b128 v[204:207], v202 offset:51200
	ds_read_b128 v[208:211], v202 offset:52224
	ds_read_b128 v[212:215], v202 offset:53248
	ds_read_b128 v[216:219], v202 offset:54272
	ds_read_b128 v[228:231], v202 offset:55296
	ds_read_b128 v[232:235], v202 offset:56320
	global_load_lds_dwordx4 v174, s[52:53]
	s_add_i32 m0, s56, 0x2000
	s_add_u32 s34, s34, 0x44000
	global_load_lds_dwordx4 v0, s[52:53]
	s_addc_u32 s35, s35, 0
	s_add_i32 s52, vcc_hi, s58
	s_mov_b32 m0, s52
	s_nop 0
	global_load_lds_dwordx4 v174, s[34:35]
	s_add_i32 m0, s52, 0x2000
	s_nop 0
	global_load_lds_dwordx4 v0, s[34:35]
	s_mov_b32 m0, s71
	s_nop 0
	global_load_lds_dwordx4 v176, s[100:101]
	s_mov_b32 m0, s76
	s_nop 0
	global_load_lds_dwordx4 v172, s[100:101]
	s_waitcnt vmcnt(8)
	s_waitcnt lgkmcnt(0)
	s_barrier
	v_mfma_f32_16x16x32_bf16 v[64:67], v[116:119], v[190:193], v[64:67]
	v_mfma_f32_16x16x32_bf16 v[64:67], v[120:123], v[194:197], v[64:67]
	v_mfma_f32_16x16x32_bf16 v[60:63], v[136:139], v[194:197], v[60:63]
	v_mfma_f32_16x16x32_bf16 v[60:63], v[124:127], v[190:193], v[60:63]
	v_mfma_f32_16x16x32_bf16 v[44:47], v[124:127], v[204:207], v[44:47]
	v_mfma_f32_16x16x32_bf16 v[44:47], v[136:139], v[208:211], v[44:47]
	v_mfma_f32_16x16x32_bf16 v[48:51], v[120:123], v[208:211], v[48:51]
	v_mfma_f32_16x16x32_bf16 v[48:51], v[116:119], v[204:207], v[48:51]
	v_mfma_f32_16x16x32_bf16 v[32:35], v[116:119], v[212:215], v[32:35]
	v_mfma_f32_16x16x32_bf16 v[32:35], v[120:123], v[216:219], v[32:35]
	v_mfma_f32_16x16x32_bf16 v[28:31], v[136:139], v[216:219], v[28:31]
	v_mfma_f32_16x16x32_bf16 v[28:31], v[124:127], v[212:215], v[28:31]
	v_mfma_f32_16x16x32_bf16 v[12:15], v[124:127], v[228:231], v[12:15]
	v_mfma_f32_16x16x32_bf16 v[12:15], v[136:139], v[232:235], v[12:15]
	v_mfma_f32_16x16x32_bf16 v[16:19], v[120:123], v[232:235], v[16:19]
	v_mfma_f32_16x16x32_bf16 v[16:19], v[116:119], v[228:231], v[16:19]
	v_mfma_f32_16x16x32_bf16 v[56:59], v[148:151], v[190:193], v[56:59]
	v_mfma_f32_16x16x32_bf16 v[56:59], v[152:155], v[194:197], v[56:59]
	v_mfma_f32_16x16x32_bf16 v[52:55], v[186:189], v[194:197], v[52:55]
	v_mfma_f32_16x16x32_bf16 v[52:55], v[182:185], v[190:193], v[52:55]
	v_mfma_f32_16x16x32_bf16 v[36:39], v[182:185], v[204:207], v[36:39]
	v_mfma_f32_16x16x32_bf16 v[36:39], v[186:189], v[208:211], v[36:39]
	v_mfma_f32_16x16x32_bf16 v[40:43], v[152:155], v[208:211], v[40:43]
	v_mfma_f32_16x16x32_bf16 v[40:43], v[148:151], v[204:207], v[40:43]
	v_mfma_f32_16x16x32_bf16 v[24:27], v[148:151], v[212:215], v[24:27]
	v_mfma_f32_16x16x32_bf16 v[24:27], v[152:155], v[216:219], v[24:27]
	v_mfma_f32_16x16x32_bf16 v[20:23], v[186:189], v[216:219], v[20:23]
	v_mfma_f32_16x16x32_bf16 v[20:23], v[182:185], v[212:215], v[20:23]
	v_mfma_f32_16x16x32_bf16 v[4:7], v[182:185], v[228:231], v[4:7]
	v_mfma_f32_16x16x32_bf16 v[4:7], v[186:189], v[232:235], v[4:7]
	v_mfma_f32_16x16x32_bf16 v[8:11], v[152:155], v[232:235], v[8:11]
	v_mfma_f32_16x16x32_bf16 v[8:11], v[148:151], v[228:231], v[8:11]
	s_barrier
	s_add_u32 s49, s49, 0x80000
	s_addc_u32 s97, s97, 0
	s_add_u32 s42, s42, 0x100
	s_addc_u32 s43, s43, 0
	s_cmp_ge_u32 vcc_lo, s69
	s_mov_b32 s34, vcc_lo
	s_cbranch_scc0 .LBB0_559
	s_setprio 0
	s_and_b64 vcc, exec, s[46:47]
	s_cbranch_vccz .LBB0_562
	s_barrier
